# attention phase A: 48 ds_bpermute butterfly hops replaced by DPP row ops (bitwise same sums)
# speedup vs baseline: 1.0089x; 1.0026x over previous
; #define LAS __attribute__((address_space(3)))
; __device__ __forceinline__ float shx(float v, int lane, int mask) { return __int_as_float(__builtin_amdgcn_ds_bpermute((lane ^ mask) << 2, __float_as_int(v))); }
; __device__ __forceinline__ unsigned cvt_pk_bf16(float lo, float hi) { unsigned r; asm volatile("v_cvt_pk_bf16_f32 %0, %1, %2" : "=v"(r) : "v"(lo), "v"(hi)); return r; }
; __device__ __forceinline__ float bflo(unsigned u) { return __uint_as_float(u << 16); }
; __device__ __forceinline__ float bfhi(unsigned u) { return __uint_as_float(u & 0xffff0000u); }
; __device__ __forceinline__ void attn_stream(const int wv, LAS unsigned char* lds, unsigned ldsb, const float* __restrict__ qng, const float* __restrict__ kng, const bf16_t* __restrict__ qkvr, bf16_t* __restrict__ og, float* __restrict__ lse, ...
;     ...
;         ATTN_GEOM(item)
;         const int inext = item + stride;
;         {
;             float gq[8], gk[8];
;             int c8 = c16 * 8; asm volatile("" : "+v"(c8));
; #pragma unroll
;             for (int j = 0; j < 8; ++j) { gq[j] = qng[hh * 128 + c8 + j] * 0.08838834764831845f; gk[j] = kng[hh * 128 + c8 + j]; }
; #pragma unroll
;             for (int it = 0; it < 12; ++it) {
;                 const u32x4 v = it < 4 ? qr[it] : kr[it - 4];
;                 float f[8] = {bflo(v.x), bfhi(v.x), bflo(v.y), bfhi(v.y), bflo(v.z), bfhi(v.z), bflo(v.w), bfhi(v.w)};
;                 float ss = 0.f;
; #pragma unroll
;                 for (int j = 0; j < 8; ++j) ss += f[j] * f[j];
;                 ss += shx(ss, lane, 1); ss += shx(ss, lane, 2); ss += shx(ss, lane, 4); ss += shx(ss, lane, 8);
;                 const float rs = rsqrtf(ss * (1.0f / 128.0f) + EPS);
; #pragma unroll
;                 for (int j = 0; j < 8; ++j) f[j] *= rs * (it < 4 ? gq[j] : gk[j]);
;                 u32x4 o; o.x = cvt_pk_bf16(f[0], f[1]); o.y = cvt_pk_bf16(f[2], f[3]); o.z = cvt_pk_bf16(f[4], f[5]); o.w = cvt_pk_bf16(f[6], f[7]);
;                 if (it < 4) *(LAS u32x4*)(lds + QI + (rr + 32 * it) * PA + c16 * 16) = o;
;                 else *(LAS u32x4*)(lds + KI + (rr + 32 * (it - 4)) * PA + c16 * 16) = o;
;             }
.LBB0_329:
	s_ashr_i32 s94, s82, 6
	s_and_b32 s19, s82, 63
	s_and_b32 s10, s82, 0xffffff00
	s_cmpk_eq_i32 s10, 0x100
	s_cselect_b64 s[96:97], -1, 0
	s_and_b64 s[10:11], s[96:97], exec
	s_cselect_b32 s18, 2, 4
	s_cmpk_lt_u32 s82, 0x100
	s_cselect_b64 s[10:11], -1, 0
	s_and_b64 s[12:13], s[10:11], exec
	s_cselect_b32 s18, 0, s18
	v_mov_b32_e32 v1, v104
	s_lshl_b32 s92, s94, 7
	s_waitcnt vmcnt(0)
	v_and_b32_e32 v74, 0xffff0000, v4
	v_add_u32_e32 v2, s92, v1
	v_ashrrev_i32_e32 v3, 31, v2
	v_lshlrev_b64 v[2:3], 2, v[2:3]
	s_waitcnt lgkmcnt(0)
	v_lshl_add_u64 v[52:53], s[84:85], 0, v[2:3]
	global_load_dwordx4 v[60:63], v[52:53], off offset:16
	global_load_dwordx4 v[70:73], v[52:53], off
	v_lshl_add_u64 v[2:3], s[86:87], 0, v[2:3]
	global_load_dwordx4 v[52:55], v[2:3], off offset:16
	global_load_dwordx4 v[56:59], v[2:3], off
	v_and_b32_e32 v2, 0xffff0000, v5
	v_lshlrev_b32_e32 v3, 16, v5
	s_lshr_b32 s12, 64, s18
	s_add_i32 s12, s12, -1
	s_and_b32 s95, s12, s19
	s_lshl_b32 s20, s95, 7
	s_xor_b32 s13, s18, 6
	s_lshr_b32 s19, s19, s13
	s_ashr_i32 s93, s92, 31
	s_waitcnt vmcnt(3)
	v_mul_f32_e32 v64, 0x3db504f3, v62
	s_waitcnt vmcnt(2)
	v_mul_f32_e32 v67, 0x3db504f3, v70
	v_mul_f32_e32 v70, 0x3db504f3, v71
	v_lshlrev_b32_e32 v71, 16, v4
	v_mul_f32_e32 v62, v74, v74
	v_mul_f32_e32 v66, 0x3db504f3, v60
	v_mul_f32_e32 v65, 0x3db504f3, v61
	v_fmac_f32_e32 v62, v71, v71
	v_pk_mul_f32 v[60:61], v[2:3], v[2:3]
	v_mul_f32_e32 v69, 0x3db504f3, v72
	v_add_f32_e32 v61, v61, v62
	v_add_f32_e32 v72, v60, v61
	v_and_b32_e32 v60, 0xffff0000, v6
	v_lshlrev_b32_e32 v61, 16, v6
	v_mul_f32_e32 v1, 0x3db504f3, v63
	v_pk_mul_f32 v[62:63], v[60:61], v[60:61]
	v_mul_f32_e32 v68, 0x3db504f3, v73
	v_add_f32_e32 v63, v63, v72
	v_add_f32_e32 v75, v62, v63
	v_and_b32_e32 v62, 0xffff0000, v7
	v_lshlrev_b32_e32 v63, 16, v7
	v_pk_mul_f32 v[72:73], v[62:63], v[62:63]
	s_nop 0
	v_add_f32_e32 v73, v73, v75
	v_add_f32_e32 v72, v72, v73
	s_nop 1
	v_add_f32_dpp v72, v72, v72 quad_perm:[1,0,3,2] row_mask:0xf bank_mask:0xf
	s_nop 1
	v_add_f32_dpp v72, v72, v72 quad_perm:[2,3,0,1] row_mask:0xf bank_mask:0xf
	s_nop 1
	v_add_f32_dpp v72, v72, v72 row_half_mirror row_mask:0xf bank_mask:0xf
	s_nop 1
	v_add_f32_dpp v72, v72, v72 row_mirror row_mask:0xf bank_mask:0xf
	v_fmamk_f32 v72, v72, 0x3c000000, v185
	v_cmp_gt_f32_e32 vcc, s36, v72
	v_mul_f32_e32 v73, 0x4b800000, v72
	s_nop 0
	v_cndmask_b32_e32 v72, v72, v73, vcc
	v_rsq_f32_e32 v72, v72
	s_nop 0
	v_mul_f32_e32 v73, 0x45800000, v72
	v_cndmask_b32_e32 v72, v72, v73, vcc
	v_mul_f32_e32 v73, v67, v72
	v_mul_f32_e32 v71, v73, v71
	v_mul_f32_e32 v73, v70, v72
	v_mul_f32_e32 v73, v73, v74
	v_mul_f32_e32 v74, v69, v72
	v_mul_f32_e32 v3, v74, v3
	v_mul_f32_e32 v74, v68, v72
	v_mul_f32_e32 v2, v74, v2
	v_mul_f32_e32 v74, v66, v72
	v_mul_f32_e32 v74, v74, v61
	v_mul_f32_e32 v61, v65, v72
	v_mul_f32_e32 v75, v61, v60
	v_mul_f32_e32 v60, v64, v72
	v_mul_f32_e32 v63, v60, v63
	v_mul_f32_e32 v60, v1, v72
	v_mul_f32_e32 v72, v60, v62
	v_cvt_pk_bf16_f32 v60, v71, v73
	v_cvt_pk_bf16_f32 v61, v3, v2
	v_cvt_pk_bf16_f32 v62, v74, v75
	v_and_b32_e32 v74, 0xffff0000, v8
	v_cvt_pk_bf16_f32 v63, v63, v72
	ds_write_b128 v108, v[60:63]
	v_lshlrev_b32_e32 v71, 16, v8
	v_mul_f32_e32 v62, v74, v74
	v_and_b32_e32 v2, 0xffff0000, v9
	v_lshlrev_b32_e32 v3, 16, v9
	v_fmac_f32_e32 v62, v71, v71
	v_pk_mul_f32 v[60:61], v[2:3], v[2:3]
	s_nop 0
	v_add_f32_e32 v61, v61, v62
	v_add_f32_e32 v72, v60, v61
	v_and_b32_e32 v60, 0xffff0000, v10
	v_lshlrev_b32_e32 v61, 16, v10
	v_pk_mul_f32 v[62:63], v[60:61], v[60:61]
	s_nop 0
	v_add_f32_e32 v63, v63, v72
	v_add_f32_e32 v75, v62, v63
	v_and_b32_e32 v62, 0xffff0000, v11
	v_lshlrev_b32_e32 v63, 16, v11
	v_pk_mul_f32 v[72:73], v[62:63], v[62:63]
	s_nop 0
	v_add_f32_e32 v73, v73, v75
	v_add_f32_e32 v72, v72, v73
	s_nop 1
	v_add_f32_dpp v72, v72, v72 quad_perm:[1,0,3,2] row_mask:0xf bank_mask:0xf
	s_nop 1
	v_add_f32_dpp v72, v72, v72 quad_perm:[2,3,0,1] row_mask:0xf bank_mask:0xf
	s_nop 1
	v_add_f32_dpp v72, v72, v72 row_half_mirror row_mask:0xf bank_mask:0xf
	s_nop 1
	v_add_f32_dpp v72, v72, v72 row_mirror row_mask:0xf bank_mask:0xf
	v_fmamk_f32 v72, v72, 0x3c000000, v185
	v_cmp_gt_f32_e32 vcc, s36, v72
	v_mul_f32_e32 v73, 0x4b800000, v72
	s_nop 0
	v_cndmask_b32_e32 v72, v72, v73, vcc
	v_rsq_f32_e32 v72, v72
	s_nop 0
	v_mul_f32_e32 v73, 0x45800000, v72
	v_cndmask_b32_e32 v72, v72, v73, vcc
	v_mul_f32_e32 v73, v67, v72
	v_mul_f32_e32 v71, v73, v71
	v_mul_f32_e32 v73, v70, v72
	v_mul_f32_e32 v73, v73, v74
	v_mul_f32_e32 v74, v69, v72
	v_mul_f32_e32 v3, v74, v3
	v_mul_f32_e32 v74, v68, v72
	v_mul_f32_e32 v2, v74, v2
	v_mul_f32_e32 v74, v66, v72
	v_mul_f32_e32 v74, v74, v61
	v_mul_f32_e32 v61, v65, v72
	v_mul_f32_e32 v75, v61, v60
	v_mul_f32_e32 v60, v64, v72
	v_mul_f32_e32 v63, v60, v63
	v_mul_f32_e32 v60, v1, v72
	v_mul_f32_e32 v72, v60, v62
	v_cvt_pk_bf16_f32 v60, v71, v73
	v_cvt_pk_bf16_f32 v61, v3, v2
	v_cvt_pk_bf16_f32 v62, v74, v75
	v_and_b32_e32 v74, 0xffff0000, v12
	v_cvt_pk_bf16_f32 v63, v63, v72
	ds_write_b128 v108, v[60:63] offset:8704
	v_lshlrev_b32_e32 v71, 16, v12
	v_mul_f32_e32 v62, v74, v74
	v_and_b32_e32 v2, 0xffff0000, v13
	v_lshlrev_b32_e32 v3, 16, v13
	v_fmac_f32_e32 v62, v71, v71
	v_pk_mul_f32 v[60:61], v[2:3], v[2:3]
	s_nop 0
	v_add_f32_e32 v61, v61, v62
	v_add_f32_e32 v72, v60, v61
	v_and_b32_e32 v60, 0xffff0000, v14
	v_lshlrev_b32_e32 v61, 16, v14
	v_pk_mul_f32 v[62:63], v[60:61], v[60:61]
	s_nop 0
	v_add_f32_e32 v63, v63, v72
	v_add_f32_e32 v75, v62, v63
	v_and_b32_e32 v62, 0xffff0000, v15
	v_lshlrev_b32_e32 v63, 16, v15
	v_pk_mul_f32 v[72:73], v[62:63], v[62:63]
	s_nop 0
	v_add_f32_e32 v73, v73, v75
; #define LAS __attribute__((address_space(3)))
; __device__ __forceinline__ float shx(float v, int lane, int mask) { return __int_as_float(__builtin_amdgcn_ds_bpermute((lane ^ mask) << 2, __float_as_int(v))); }
; __device__ __forceinline__ unsigned cvt_pk_bf16(float lo, float hi) { unsigned r; asm volatile("v_cvt_pk_bf16_f32 %0, %1, %2" : "=v"(r) : "v"(lo), "v"(hi)); return r; }
; __device__ __forceinline__ float bflo(unsigned u) { return __uint_as_float(u << 16); }
; __device__ __forceinline__ float bfhi(unsigned u) { return __uint_as_float(u & 0xffff0000u); }
; __device__ __forceinline__ void attn_stream(const int wv, LAS unsigned char* lds, unsigned ldsb, const float* __restrict__ qng, const float* __restrict__ kng, const bf16_t* __restrict__ qkvr, bf16_t* __restrict__ og, float* __restrict__ lse, ...
;     ...
;             for (int it = 0; it < 12; ++it) {
;                 const u32x4 v = it < 4 ? qr[it] : kr[it - 4];
;                 float f[8] = {bflo(v.x), bfhi(v.x), bflo(v.y), bfhi(v.y), bflo(v.z), bfhi(v.z), bflo(v.w), bfhi(v.w)};
;                 float ss = 0.f;
; #pragma unroll
;                 for (int j = 0; j < 8; ++j) ss += f[j] * f[j];
;                 ss += shx(ss, lane, 1); ss += shx(ss, lane, 2); ss += shx(ss, lane, 4); ss += shx(ss, lane, 8);
;                 const float rs = rsqrtf(ss * (1.0f / 128.0f) + EPS);
; #pragma unroll
;                 for (int j = 0; j < 8; ++j) f[j] *= rs * (it < 4 ? gq[j] : gk[j]);
;                 u32x4 o; o.x = cvt_pk_bf16(f[0], f[1]); o.y = cvt_pk_bf16(f[2], f[3]); o.z = cvt_pk_bf16(f[4], f[5]); o.w = cvt_pk_bf16(f[6], f[7]);
;                 if (it < 4) *(LAS u32x4*)(lds + QI + (rr + 32 * it) * PA + c16 * 16) = o;
;                 else *(LAS u32x4*)(lds + KI + (rr + 32 * (it - 4)) * PA + c16 * 16) = o;
;             }
	v_add_f32_e32 v72, v72, v73
	s_nop 1
	v_add_f32_dpp v72, v72, v72 quad_perm:[1,0,3,2] row_mask:0xf bank_mask:0xf
	s_nop 1
	v_add_f32_dpp v72, v72, v72 quad_perm:[2,3,0,1] row_mask:0xf bank_mask:0xf
	s_nop 1
	v_add_f32_dpp v72, v72, v72 row_half_mirror row_mask:0xf bank_mask:0xf
	s_nop 1
	v_add_f32_dpp v72, v72, v72 row_mirror row_mask:0xf bank_mask:0xf
	v_fmamk_f32 v72, v72, 0x3c000000, v185
	v_cmp_gt_f32_e32 vcc, s36, v72
	v_mul_f32_e32 v73, 0x4b800000, v72
	s_nop 0
	v_cndmask_b32_e32 v72, v72, v73, vcc
	v_rsq_f32_e32 v72, v72
	s_nop 0
	v_mul_f32_e32 v73, 0x45800000, v72
	v_cndmask_b32_e32 v72, v72, v73, vcc
	v_mul_f32_e32 v73, v67, v72
	v_mul_f32_e32 v71, v73, v71
	v_mul_f32_e32 v73, v70, v72
	v_mul_f32_e32 v73, v73, v74
	v_mul_f32_e32 v74, v69, v72
	v_mul_f32_e32 v3, v74, v3
	v_mul_f32_e32 v74, v68, v72
	v_mul_f32_e32 v2, v74, v2
	v_mul_f32_e32 v74, v66, v72
	v_mul_f32_e32 v74, v74, v61
	v_mul_f32_e32 v61, v65, v72
	v_mul_f32_e32 v75, v61, v60
	v_mul_f32_e32 v60, v64, v72
	v_mul_f32_e32 v63, v60, v63
	v_mul_f32_e32 v60, v1, v72
	v_mul_f32_e32 v72, v60, v62
	v_cvt_pk_bf16_f32 v60, v71, v73
	v_cvt_pk_bf16_f32 v61, v3, v2
	v_cvt_pk_bf16_f32 v62, v74, v75
	v_and_b32_e32 v74, 0xffff0000, v16
	v_cvt_pk_bf16_f32 v63, v63, v72
	ds_write_b128 v108, v[60:63] offset:17408
	v_lshlrev_b32_e32 v71, 16, v16
	v_mul_f32_e32 v62, v74, v74
	v_and_b32_e32 v2, 0xffff0000, v17
	v_lshlrev_b32_e32 v3, 16, v17
	v_fmac_f32_e32 v62, v71, v71
	v_pk_mul_f32 v[60:61], v[2:3], v[2:3]
	s_nop 0
	v_add_f32_e32 v61, v61, v62
	v_add_f32_e32 v72, v60, v61
	v_and_b32_e32 v60, 0xffff0000, v18
	v_lshlrev_b32_e32 v61, 16, v18
	v_pk_mul_f32 v[62:63], v[60:61], v[60:61]
	s_nop 0
	v_add_f32_e32 v63, v63, v72
	v_add_f32_e32 v75, v62, v63
	v_and_b32_e32 v62, 0xffff0000, v19
	v_lshlrev_b32_e32 v63, 16, v19
	v_pk_mul_f32 v[72:73], v[62:63], v[62:63]
	s_nop 0
	v_add_f32_e32 v73, v73, v75
	v_add_f32_e32 v72, v72, v73
	s_nop 1
	v_add_f32_dpp v72, v72, v72 quad_perm:[1,0,3,2] row_mask:0xf bank_mask:0xf
	s_nop 1
	v_add_f32_dpp v72, v72, v72 quad_perm:[2,3,0,1] row_mask:0xf bank_mask:0xf
	s_nop 1
	v_add_f32_dpp v72, v72, v72 row_half_mirror row_mask:0xf bank_mask:0xf
	s_nop 1
	v_add_f32_dpp v72, v72, v72 row_mirror row_mask:0xf bank_mask:0xf
	v_fmamk_f32 v72, v72, 0x3c000000, v185
	v_cmp_gt_f32_e32 vcc, s36, v72
	v_mul_f32_e32 v73, 0x4b800000, v72
	s_nop 0
	v_cndmask_b32_e32 v72, v72, v73, vcc
	v_rsq_f32_e32 v72, v72
	s_nop 0
	v_mul_f32_e32 v73, 0x45800000, v72
	v_cndmask_b32_e32 v72, v72, v73, vcc
	v_mul_f32_e32 v66, v66, v72
	v_mul_f32_e32 v66, v66, v61
	v_mul_f32_e32 v61, v65, v72
	v_mul_f32_e32 v67, v67, v72
	v_mul_f32_e32 v70, v70, v72
	v_mul_f32_e32 v69, v69, v72
	v_mul_f32_e32 v68, v68, v72
	v_mul_f32_e32 v65, v61, v60
	v_mul_f32_e32 v60, v64, v72
	v_mul_f32_e32 v1, v1, v72
	v_mul_f32_e32 v67, v67, v71
	v_mul_f32_e32 v70, v70, v74
	v_mul_f32_e32 v3, v69, v3
	v_mul_f32_e32 v2, v68, v2
	v_mul_f32_e32 v63, v60, v63
	v_mul_f32_e32 v1, v1, v62
	v_cvt_pk_bf16_f32 v60, v67, v70
	v_cvt_pk_bf16_f32 v61, v3, v2
	v_cvt_pk_bf16_f32 v62, v66, v65
	v_and_b32_e32 v66, 0xffff0000, v24
	v_cvt_pk_bf16_f32 v63, v63, v1
	ds_write_b128 v108, v[60:63] offset:26112
	v_lshlrev_b32_e32 v1, 16, v24
	v_mul_f32_e32 v62, v66, v66
	v_and_b32_e32 v2, 0xffff0000, v25
	v_lshlrev_b32_e32 v3, 16, v25
	v_fmac_f32_e32 v62, v1, v1
	v_pk_mul_f32 v[60:61], v[2:3], v[2:3]
	s_nop 0
	v_add_f32_e32 v61, v61, v62
	v_add_f32_e32 v64, v60, v61
	v_and_b32_e32 v60, 0xffff0000, v26
	v_lshlrev_b32_e32 v61, 16, v26
	v_pk_mul_f32 v[62:63], v[60:61], v[60:61]
	s_nop 0
	v_add_f32_e32 v63, v63, v64
	v_add_f32_e32 v67, v62, v63
	v_and_b32_e32 v62, 0xffff0000, v27
	v_lshlrev_b32_e32 v63, 16, v27
	v_pk_mul_f32 v[64:65], v[62:63], v[62:63]
	s_nop 0
	v_add_f32_e32 v65, v65, v67
	v_add_f32_e32 v64, v64, v65
	s_nop 1
	v_add_f32_dpp v64, v64, v64 quad_perm:[1,0,3,2] row_mask:0xf bank_mask:0xf
	s_nop 1
	v_add_f32_dpp v64, v64, v64 quad_perm:[2,3,0,1] row_mask:0xf bank_mask:0xf
	s_nop 1
	v_add_f32_dpp v64, v64, v64 row_half_mirror row_mask:0xf bank_mask:0xf
	s_nop 1
	v_add_f32_dpp v64, v64, v64 row_mirror row_mask:0xf bank_mask:0xf
	v_fmamk_f32 v64, v64, 0x3c000000, v185
	v_cmp_gt_f32_e32 vcc, s36, v64
	v_mul_f32_e32 v65, 0x4b800000, v64
	s_nop 0
	v_cndmask_b32_e32 v64, v64, v65, vcc
	v_rsq_f32_e32 v64, v64
	s_nop 0
	v_mul_f32_e32 v65, 0x45800000, v64
	v_cndmask_b32_e32 v64, v64, v65, vcc
	s_waitcnt vmcnt(0)
; #define LAS __attribute__((address_space(3)))
; __device__ __forceinline__ float shx(float v, int lane, int mask) { return __int_as_float(__builtin_amdgcn_ds_bpermute((lane ^ mask) << 2, __float_as_int(v))); }
; __device__ __forceinline__ unsigned cvt_pk_bf16(float lo, float hi) { unsigned r; asm volatile("v_cvt_pk_bf16_f32 %0, %1, %2" : "=v"(r) : "v"(lo), "v"(hi)); return r; }
; __device__ __forceinline__ float bflo(unsigned u) { return __uint_as_float(u << 16); }
; __device__ __forceinline__ float bfhi(unsigned u) { return __uint_as_float(u & 0xffff0000u); }
; __device__ __forceinline__ void attn_stream(const int wv, LAS unsigned char* lds, unsigned ldsb, const float* __restrict__ qng, const float* __restrict__ kng, const bf16_t* __restrict__ qkvr, bf16_t* __restrict__ og, float* __restrict__ lse, ...
;     ...
;             for (int it = 0; it < 12; ++it) {
;                 const u32x4 v = it < 4 ? qr[it] : kr[it - 4];
;                 float f[8] = {bflo(v.x), bfhi(v.x), bflo(v.y), bfhi(v.y), bflo(v.z), bfhi(v.z), bflo(v.w), bfhi(v.w)};
;                 float ss = 0.f;
; #pragma unroll
;                 for (int j = 0; j < 8; ++j) ss += f[j] * f[j];
;                 ss += shx(ss, lane, 1); ss += shx(ss, lane, 2); ss += shx(ss, lane, 4); ss += shx(ss, lane, 8);
;                 const float rs = rsqrtf(ss * (1.0f / 128.0f) + EPS);
; #pragma unroll
;                 for (int j = 0; j < 8; ++j) f[j] *= rs * (it < 4 ? gq[j] : gk[j]);
;                 u32x4 o; o.x = cvt_pk_bf16(f[0], f[1]); o.y = cvt_pk_bf16(f[2], f[3]); o.z = cvt_pk_bf16(f[4], f[5]); o.w = cvt_pk_bf16(f[6], f[7]);
;                 if (it < 4) *(LAS u32x4*)(lds + QI + (rr + 32 * it) * PA + c16 * 16) = o;
;                 else *(LAS u32x4*)(lds + KI + (rr + 32 * (it - 4)) * PA + c16 * 16) = o;
;             }
	v_mul_f32_e32 v65, v56, v64
	v_mul_f32_e32 v1, v65, v1
	v_mul_f32_e32 v65, v57, v64
	v_mul_f32_e32 v65, v65, v66
	v_mul_f32_e32 v66, v58, v64
	v_mul_f32_e32 v3, v66, v3
	v_mul_f32_e32 v66, v59, v64
	v_mul_f32_e32 v2, v66, v2
	v_mul_f32_e32 v66, v52, v64
	v_mul_f32_e32 v66, v66, v61
	v_mul_f32_e32 v61, v53, v64
	v_mul_f32_e32 v67, v61, v60
	v_mul_f32_e32 v60, v54, v64
	v_mul_f32_e32 v63, v60, v63
	v_mul_f32_e32 v60, v55, v64
	v_mul_f32_e32 v64, v60, v62
	v_cvt_pk_bf16_f32 v60, v1, v65
	v_cvt_pk_bf16_f32 v61, v3, v2
	v_cvt_pk_bf16_f32 v62, v66, v67
	v_and_b32_e32 v66, 0xffff0000, v20
	v_cvt_pk_bf16_f32 v63, v63, v64
	ds_write_b128 v108, v[60:63] offset:34816
	v_lshlrev_b32_e32 v1, 16, v20
	v_mul_f32_e32 v62, v66, v66
	v_and_b32_e32 v2, 0xffff0000, v21
	v_lshlrev_b32_e32 v3, 16, v21
	v_fmac_f32_e32 v62, v1, v1
	v_pk_mul_f32 v[60:61], v[2:3], v[2:3]
	s_nop 0
	v_add_f32_e32 v61, v61, v62
	v_add_f32_e32 v64, v60, v61
	v_and_b32_e32 v60, 0xffff0000, v22
	v_lshlrev_b32_e32 v61, 16, v22
	v_pk_mul_f32 v[62:63], v[60:61], v[60:61]
	s_nop 0
	v_add_f32_e32 v63, v63, v64
	v_add_f32_e32 v67, v62, v63
	v_and_b32_e32 v62, 0xffff0000, v23
	v_lshlrev_b32_e32 v63, 16, v23
	v_pk_mul_f32 v[64:65], v[62:63], v[62:63]
	s_nop 0
	v_add_f32_e32 v65, v65, v67
	v_add_f32_e32 v64, v64, v65
	s_nop 1
	v_add_f32_dpp v64, v64, v64 quad_perm:[1,0,3,2] row_mask:0xf bank_mask:0xf
	s_nop 1
	v_add_f32_dpp v64, v64, v64 quad_perm:[2,3,0,1] row_mask:0xf bank_mask:0xf
	s_nop 1
	v_add_f32_dpp v64, v64, v64 row_half_mirror row_mask:0xf bank_mask:0xf
	s_nop 1
	v_add_f32_dpp v64, v64, v64 row_mirror row_mask:0xf bank_mask:0xf
	v_fmamk_f32 v64, v64, 0x3c000000, v185
	v_cmp_gt_f32_e32 vcc, s36, v64
	v_mul_f32_e32 v65, 0x4b800000, v64
	s_nop 0
	v_cndmask_b32_e32 v64, v64, v65, vcc
	v_rsq_f32_e32 v64, v64
	s_nop 0
	v_mul_f32_e32 v65, 0x45800000, v64
	v_cndmask_b32_e32 v64, v64, v65, vcc
	v_mul_f32_e32 v65, v56, v64
	v_mul_f32_e32 v1, v65, v1
	v_mul_f32_e32 v65, v57, v64
	v_mul_f32_e32 v65, v65, v66
	v_mul_f32_e32 v66, v58, v64
	v_mul_f32_e32 v3, v66, v3
	v_mul_f32_e32 v66, v59, v64
	v_mul_f32_e32 v2, v66, v2
	v_mul_f32_e32 v66, v52, v64
	v_mul_f32_e32 v66, v66, v61
	v_mul_f32_e32 v61, v53, v64
	v_mul_f32_e32 v67, v61, v60
	v_mul_f32_e32 v60, v54, v64
	v_mul_f32_e32 v63, v60, v63
	v_mul_f32_e32 v60, v55, v64
	v_mul_f32_e32 v64, v60, v62
	v_cvt_pk_bf16_f32 v60, v1, v65
	v_cvt_pk_bf16_f32 v61, v3, v2
	v_cvt_pk_bf16_f32 v62, v66, v67
	v_and_b32_e32 v66, 0xffff0000, v28
	v_cvt_pk_bf16_f32 v63, v63, v64
	ds_write_b128 v108, v[60:63] offset:43520
	v_lshlrev_b32_e32 v1, 16, v28
	v_mul_f32_e32 v62, v66, v66
	v_and_b32_e32 v2, 0xffff0000, v29
	v_lshlrev_b32_e32 v3, 16, v29
	v_fmac_f32_e32 v62, v1, v1
	v_pk_mul_f32 v[60:61], v[2:3], v[2:3]
	s_nop 0
	v_add_f32_e32 v61, v61, v62
	v_add_f32_e32 v64, v60, v61
	v_and_b32_e32 v60, 0xffff0000, v30
	v_lshlrev_b32_e32 v61, 16, v30
	v_pk_mul_f32 v[62:63], v[60:61], v[60:61]
	s_nop 0
	v_add_f32_e32 v63, v63, v64
	v_add_f32_e32 v67, v62, v63
	v_and_b32_e32 v62, 0xffff0000, v31
	v_lshlrev_b32_e32 v63, 16, v31
	v_pk_mul_f32 v[64:65], v[62:63], v[62:63]
	s_nop 0
	v_add_f32_e32 v65, v65, v67
	v_add_f32_e32 v64, v64, v65
	s_nop 1
	v_add_f32_dpp v64, v64, v64 quad_perm:[1,0,3,2] row_mask:0xf bank_mask:0xf
	s_nop 1
	v_add_f32_dpp v64, v64, v64 quad_perm:[2,3,0,1] row_mask:0xf bank_mask:0xf
	s_nop 1
	v_add_f32_dpp v64, v64, v64 row_half_mirror row_mask:0xf bank_mask:0xf
	s_nop 1
	v_add_f32_dpp v64, v64, v64 row_mirror row_mask:0xf bank_mask:0xf
	v_fmamk_f32 v64, v64, 0x3c000000, v185
	v_cmp_gt_f32_e32 vcc, s36, v64
	v_mul_f32_e32 v65, 0x4b800000, v64
	s_nop 0
	v_cndmask_b32_e32 v64, v64, v65, vcc
	v_rsq_f32_e32 v64, v64
	s_nop 0
	v_mul_f32_e32 v65, 0x45800000, v64
	v_cndmask_b32_e32 v64, v64, v65, vcc
	v_mul_f32_e32 v65, v56, v64
	v_mul_f32_e32 v1, v65, v1
	v_mul_f32_e32 v65, v57, v64
	v_mul_f32_e32 v65, v65, v66
	v_mul_f32_e32 v66, v58, v64
	v_mul_f32_e32 v3, v66, v3
	v_mul_f32_e32 v66, v59, v64
	v_mul_f32_e32 v2, v66, v2
	v_mul_f32_e32 v66, v52, v64
	v_mul_f32_e32 v66, v66, v61
	v_mul_f32_e32 v61, v53, v64
	v_mul_f32_e32 v67, v61, v60
	v_mul_f32_e32 v60, v54, v64
	v_mul_f32_e32 v63, v60, v63
	v_mul_f32_e32 v60, v55, v64
	v_mul_f32_e32 v64, v60, v62
	v_cvt_pk_bf16_f32 v60, v1, v65
	v_cvt_pk_bf16_f32 v61, v3, v2
	v_cvt_pk_bf16_f32 v62, v66, v67
	v_and_b32_e32 v66, 0xffff0000, v32
	v_cvt_pk_bf16_f32 v63, v63, v64
	ds_write_b128 v108, v[60:63] offset:52224
	v_lshlrev_b32_e32 v1, 16, v32
	v_mul_f32_e32 v62, v66, v66
	v_and_b32_e32 v2, 0xffff0000, v33
	v_lshlrev_b32_e32 v3, 16, v33
	v_fmac_f32_e32 v62, v1, v1
	v_pk_mul_f32 v[60:61], v[2:3], v[2:3]
	s_nop 0
	v_add_f32_e32 v61, v61, v62
	v_add_f32_e32 v64, v60, v61
	v_and_b32_e32 v60, 0xffff0000, v34
	v_lshlrev_b32_e32 v61, 16, v34
	v_pk_mul_f32 v[62:63], v[60:61], v[60:61]
	s_nop 0
	v_add_f32_e32 v63, v63, v64
	v_add_f32_e32 v67, v62, v63
	v_and_b32_e32 v62, 0xffff0000, v35
	v_lshlrev_b32_e32 v63, 16, v35
	v_pk_mul_f32 v[64:65], v[62:63], v[62:63]
	s_nop 0
	v_add_f32_e32 v65, v65, v67
	v_add_f32_e32 v64, v64, v65
	s_nop 1
	v_add_f32_dpp v64, v64, v64 quad_perm:[1,0,3,2] row_mask:0xf bank_mask:0xf
	s_nop 1
	v_add_f32_dpp v64, v64, v64 quad_perm:[2,3,0,1] row_mask:0xf bank_mask:0xf
	s_nop 1
	v_add_f32_dpp v64, v64, v64 row_half_mirror row_mask:0xf bank_mask:0xf
	s_nop 1
	v_add_f32_dpp v64, v64, v64 row_mirror row_mask:0xf bank_mask:0xf
	v_fmamk_f32 v64, v64, 0x3c000000, v185
	v_cmp_gt_f32_e32 vcc, s36, v64
	v_mul_f32_e32 v65, 0x4b800000, v64
	s_nop 0
	v_cndmask_b32_e32 v64, v64, v65, vcc
	v_rsq_f32_e32 v64, v64
	s_nop 0
	v_mul_f32_e32 v65, 0x45800000, v64
	v_cndmask_b32_e32 v64, v64, v65, vcc
	v_mul_f32_e32 v65, v56, v64
; #define LAS __attribute__((address_space(3)))
; __device__ __forceinline__ float shx(float v, int lane, int mask) { return __int_as_float(__builtin_amdgcn_ds_bpermute((lane ^ mask) << 2, __float_as_int(v))); }
; __device__ __forceinline__ unsigned cvt_pk_bf16(float lo, float hi) { unsigned r; asm volatile("v_cvt_pk_bf16_f32 %0, %1, %2" : "=v"(r) : "v"(lo), "v"(hi)); return r; }
; __device__ __forceinline__ float bflo(unsigned u) { return __uint_as_float(u << 16); }
; __device__ __forceinline__ float bfhi(unsigned u) { return __uint_as_float(u & 0xffff0000u); }
; __device__ __forceinline__ void attn_stream(const int wv, LAS unsigned char* lds, unsigned ldsb, const float* __restrict__ qng, const float* __restrict__ kng, const bf16_t* __restrict__ qkvr, bf16_t* __restrict__ og, float* __restrict__ lse, ...
;     ...
;             for (int it = 0; it < 12; ++it) {
;                 const u32x4 v = it < 4 ? qr[it] : kr[it - 4];
;                 float f[8] = {bflo(v.x), bfhi(v.x), bflo(v.y), bfhi(v.y), bflo(v.z), bfhi(v.z), bflo(v.w), bfhi(v.w)};
;                 float ss = 0.f;
; #pragma unroll
;                 for (int j = 0; j < 8; ++j) ss += f[j] * f[j];
;                 ss += shx(ss, lane, 1); ss += shx(ss, lane, 2); ss += shx(ss, lane, 4); ss += shx(ss, lane, 8);
;                 const float rs = rsqrtf(ss * (1.0f / 128.0f) + EPS);
; #pragma unroll
;                 for (int j = 0; j < 8; ++j) f[j] *= rs * (it < 4 ? gq[j] : gk[j]);
;                 u32x4 o; o.x = cvt_pk_bf16(f[0], f[1]); o.y = cvt_pk_bf16(f[2], f[3]); o.z = cvt_pk_bf16(f[4], f[5]); o.w = cvt_pk_bf16(f[6], f[7]);
;                 if (it < 4) *(LAS u32x4*)(lds + QI + (rr + 32 * it) * PA + c16 * 16) = o;
;                 else *(LAS u32x4*)(lds + KI + (rr + 32 * (it - 4)) * PA + c16 * 16) = o;
;             }
	v_mul_f32_e32 v1, v65, v1
	v_mul_f32_e32 v65, v57, v64
	v_mul_f32_e32 v65, v65, v66
	v_mul_f32_e32 v66, v58, v64
	v_mul_f32_e32 v3, v66, v3
	v_mul_f32_e32 v66, v59, v64
	v_mul_f32_e32 v2, v66, v2
	v_mul_f32_e32 v66, v52, v64
	v_mul_f32_e32 v66, v66, v61
	v_mul_f32_e32 v61, v53, v64
	v_mul_f32_e32 v67, v61, v60
	v_mul_f32_e32 v60, v54, v64
	v_mul_f32_e32 v63, v60, v63
	v_mul_f32_e32 v60, v55, v64
	v_mul_f32_e32 v64, v60, v62
	v_cvt_pk_bf16_f32 v60, v1, v65
	v_cvt_pk_bf16_f32 v61, v3, v2
	v_cvt_pk_bf16_f32 v62, v66, v67
	v_and_b32_e32 v66, 0xffff0000, v36
	v_cvt_pk_bf16_f32 v63, v63, v64
	ds_write_b128 v108, v[60:63] offset:60928
	v_lshlrev_b32_e32 v1, 16, v36
	v_mul_f32_e32 v62, v66, v66
	v_and_b32_e32 v2, 0xffff0000, v37
	v_lshlrev_b32_e32 v3, 16, v37
	v_fmac_f32_e32 v62, v1, v1
	v_pk_mul_f32 v[60:61], v[2:3], v[2:3]
	s_nop 0
	v_add_f32_e32 v61, v61, v62
	v_add_f32_e32 v64, v60, v61
	v_and_b32_e32 v60, 0xffff0000, v38
	v_lshlrev_b32_e32 v61, 16, v38
	v_pk_mul_f32 v[62:63], v[60:61], v[60:61]
	s_nop 0
	v_add_f32_e32 v63, v63, v64
	v_add_f32_e32 v67, v62, v63
	v_and_b32_e32 v62, 0xffff0000, v39
	v_lshlrev_b32_e32 v63, 16, v39
	v_pk_mul_f32 v[64:65], v[62:63], v[62:63]
	s_nop 0
	v_add_f32_e32 v65, v65, v67
	v_add_f32_e32 v64, v64, v65
	s_nop 1
	v_add_f32_dpp v64, v64, v64 quad_perm:[1,0,3,2] row_mask:0xf bank_mask:0xf
	s_nop 1
	v_add_f32_dpp v64, v64, v64 quad_perm:[2,3,0,1] row_mask:0xf bank_mask:0xf
	s_nop 1
	v_add_f32_dpp v64, v64, v64 row_half_mirror row_mask:0xf bank_mask:0xf
	s_nop 1
	v_add_f32_dpp v64, v64, v64 row_mirror row_mask:0xf bank_mask:0xf
	v_fmamk_f32 v64, v64, 0x3c000000, v185
	v_cmp_gt_f32_e32 vcc, s36, v64
	v_mul_f32_e32 v65, 0x4b800000, v64
	s_nop 0
	v_cndmask_b32_e32 v64, v64, v65, vcc
	v_rsq_f32_e32 v64, v64
	s_nop 0
	v_mul_f32_e32 v65, 0x45800000, v64
	v_cndmask_b32_e32 v64, v64, v65, vcc
	v_mul_f32_e32 v65, v56, v64
	v_mul_f32_e32 v1, v65, v1
	v_mul_f32_e32 v65, v57, v64
	v_mul_f32_e32 v65, v65, v66
	v_mul_f32_e32 v66, v58, v64
	v_mul_f32_e32 v3, v66, v3
	v_mul_f32_e32 v66, v59, v64
	v_mul_f32_e32 v2, v66, v2
	v_mul_f32_e32 v66, v52, v64
	v_mul_f32_e32 v66, v66, v61
	v_mul_f32_e32 v61, v53, v64
	v_mul_f32_e32 v67, v61, v60
	v_mul_f32_e32 v60, v54, v64
	v_mul_f32_e32 v63, v60, v63
	v_mul_f32_e32 v60, v55, v64
	v_mul_f32_e32 v64, v60, v62
	v_cvt_pk_bf16_f32 v60, v1, v65
	v_cvt_pk_bf16_f32 v61, v3, v2
	v_cvt_pk_bf16_f32 v62, v66, v67
	v_and_b32_e32 v66, 0xffff0000, v40
	v_cvt_pk_bf16_f32 v63, v63, v64
	ds_write_b128 v109, v[60:63] offset:34816
	v_lshlrev_b32_e32 v1, 16, v40
	v_mul_f32_e32 v62, v66, v66
	v_and_b32_e32 v2, 0xffff0000, v41
	v_lshlrev_b32_e32 v3, 16, v41
	v_fmac_f32_e32 v62, v1, v1
	v_pk_mul_f32 v[60:61], v[2:3], v[2:3]
	s_nop 0
	v_add_f32_e32 v61, v61, v62
	v_add_f32_e32 v64, v60, v61
	v_and_b32_e32 v60, 0xffff0000, v42
	v_lshlrev_b32_e32 v61, 16, v42
	v_pk_mul_f32 v[62:63], v[60:61], v[60:61]
	s_nop 0
	v_add_f32_e32 v63, v63, v64
	v_add_f32_e32 v67, v62, v63
	v_and_b32_e32 v62, 0xffff0000, v43
	v_lshlrev_b32_e32 v63, 16, v43
	v_pk_mul_f32 v[64:65], v[62:63], v[62:63]
	s_nop 0
	v_add_f32_e32 v65, v65, v67
	v_add_f32_e32 v64, v64, v65
	s_nop 1
	v_add_f32_dpp v64, v64, v64 quad_perm:[1,0,3,2] row_mask:0xf bank_mask:0xf
	s_nop 1
	v_add_f32_dpp v64, v64, v64 quad_perm:[2,3,0,1] row_mask:0xf bank_mask:0xf
	s_nop 1
	v_add_f32_dpp v64, v64, v64 row_half_mirror row_mask:0xf bank_mask:0xf
	s_nop 1
	v_add_f32_dpp v64, v64, v64 row_mirror row_mask:0xf bank_mask:0xf
	v_fmamk_f32 v64, v64, 0x3c000000, v185
	v_cmp_gt_f32_e32 vcc, s36, v64
	v_mul_f32_e32 v65, 0x4b800000, v64
	s_nop 0
	v_cndmask_b32_e32 v64, v64, v65, vcc
	v_rsq_f32_e32 v64, v64
	s_nop 0
	v_mul_f32_e32 v65, 0x45800000, v64
	v_cndmask_b32_e32 v64, v64, v65, vcc
	v_mul_f32_e32 v65, v56, v64
	v_mul_f32_e32 v1, v65, v1
	v_mul_f32_e32 v65, v57, v64
	v_mul_f32_e32 v65, v65, v66
	v_mul_f32_e32 v66, v58, v64
	v_mul_f32_e32 v3, v66, v3
	v_mul_f32_e32 v66, v59, v64
	v_mul_f32_e32 v2, v66, v2
	v_mul_f32_e32 v66, v52, v64
	v_mul_f32_e32 v66, v66, v61
	v_mul_f32_e32 v61, v53, v64
	v_mul_f32_e32 v67, v61, v60
	v_mul_f32_e32 v60, v54, v64
	v_mul_f32_e32 v63, v60, v63
	v_mul_f32_e32 v60, v55, v64
	v_mul_f32_e32 v64, v60, v62
	v_cvt_pk_bf16_f32 v60, v1, v65
	v_cvt_pk_bf16_f32 v61, v3, v2
	v_cvt_pk_bf16_f32 v62, v66, v67
	v_and_b32_e32 v66, 0xffff0000, v44
	v_cvt_pk_bf16_f32 v63, v63, v64
	ds_write_b128 v109, v[60:63] offset:43520
	v_lshlrev_b32_e32 v1, 16, v44
; #define LAS __attribute__((address_space(3)))
; __device__ __forceinline__ float shx(float v, int lane, int mask) { return __int_as_float(__builtin_amdgcn_ds_bpermute((lane ^ mask) << 2, __float_as_int(v))); }
; __device__ __forceinline__ unsigned cvt_pk_bf16(float lo, float hi) { unsigned r; asm volatile("v_cvt_pk_bf16_f32 %0, %1, %2" : "=v"(r) : "v"(lo), "v"(hi)); return r; }
; __device__ __forceinline__ float bflo(unsigned u) { return __uint_as_float(u << 16); }
; __device__ __forceinline__ float bfhi(unsigned u) { return __uint_as_float(u & 0xffff0000u); }
; __device__ __forceinline__ void attn_stream(const int wv, LAS unsigned char* lds, unsigned ldsb, const float* __restrict__ qng, const float* __restrict__ kng, const bf16_t* __restrict__ qkvr, bf16_t* __restrict__ og, float* __restrict__ lse, ...
;     ...
;             for (int it = 0; it < 12; ++it) {
;                 const u32x4 v = it < 4 ? qr[it] : kr[it - 4];
;                 float f[8] = {bflo(v.x), bfhi(v.x), bflo(v.y), bfhi(v.y), bflo(v.z), bfhi(v.z), bflo(v.w), bfhi(v.w)};
;                 float ss = 0.f;
; #pragma unroll
;                 for (int j = 0; j < 8; ++j) ss += f[j] * f[j];
;                 ss += shx(ss, lane, 1); ss += shx(ss, lane, 2); ss += shx(ss, lane, 4); ss += shx(ss, lane, 8);
;                 const float rs = rsqrtf(ss * (1.0f / 128.0f) + EPS);
; #pragma unroll
;                 for (int j = 0; j < 8; ++j) f[j] *= rs * (it < 4 ? gq[j] : gk[j]);
;                 u32x4 o; o.x = cvt_pk_bf16(f[0], f[1]); o.y = cvt_pk_bf16(f[2], f[3]); o.z = cvt_pk_bf16(f[4], f[5]); o.w = cvt_pk_bf16(f[6], f[7]);
;                 if (it < 4) *(LAS u32x4*)(lds + QI + (rr + 32 * it) * PA + c16 * 16) = o;
;                 else *(LAS u32x4*)(lds + KI + (rr + 32 * (it - 4)) * PA + c16 * 16) = o;
;             }
;         }
;         __syncthreads();
; #pragma unroll
;         for (int it = 0; it < 8; ++it) { const int l = n * 128 - 128 + rr + 32 * it; vr[it] = (u32x4){0u, 0u, 0u, 0u};
;             if (l >= 0) vr[it] = *(const u32x4*)(qkvr + (size_t)(l * dil + r) * QKVR_LD + C_AV + hh * 128 + c16 * 8); }
	v_mul_f32_e32 v62, v66, v66
	v_and_b32_e32 v2, 0xffff0000, v45
	v_lshlrev_b32_e32 v3, 16, v45
	v_fmac_f32_e32 v62, v1, v1
	v_pk_mul_f32 v[60:61], v[2:3], v[2:3]
	s_nop 0
	v_add_f32_e32 v61, v61, v62
	v_add_f32_e32 v64, v60, v61
	v_and_b32_e32 v60, 0xffff0000, v46
	v_lshlrev_b32_e32 v61, 16, v46
	v_pk_mul_f32 v[62:63], v[60:61], v[60:61]
	s_nop 0
	v_add_f32_e32 v63, v63, v64
	v_add_f32_e32 v67, v62, v63
	v_and_b32_e32 v62, 0xffff0000, v47
	v_lshlrev_b32_e32 v63, 16, v47
	v_pk_mul_f32 v[64:65], v[62:63], v[62:63]
	s_nop 0
	v_add_f32_e32 v65, v65, v67
	v_add_f32_e32 v64, v64, v65
	s_nop 1
	v_add_f32_dpp v64, v64, v64 quad_perm:[1,0,3,2] row_mask:0xf bank_mask:0xf
	s_nop 1
	v_add_f32_dpp v64, v64, v64 quad_perm:[2,3,0,1] row_mask:0xf bank_mask:0xf
	s_nop 1
	v_add_f32_dpp v64, v64, v64 row_half_mirror row_mask:0xf bank_mask:0xf
	s_nop 1
	v_add_f32_dpp v64, v64, v64 row_mirror row_mask:0xf bank_mask:0xf
	v_fmamk_f32 v64, v64, 0x3c000000, v185
	v_cmp_gt_f32_e32 vcc, s36, v64
	v_mul_f32_e32 v65, 0x4b800000, v64
	s_nop 0
	v_cndmask_b32_e32 v64, v64, v65, vcc
	v_rsq_f32_e32 v64, v64
	s_nop 0
	v_mul_f32_e32 v65, 0x45800000, v64
	v_cndmask_b32_e32 v64, v64, v65, vcc
	v_mul_f32_e32 v65, v56, v64
	v_mul_f32_e32 v1, v65, v1
	v_mul_f32_e32 v65, v57, v64
	v_mul_f32_e32 v65, v65, v66
	v_mul_f32_e32 v66, v58, v64
	v_mul_f32_e32 v3, v66, v3
	v_mul_f32_e32 v66, v59, v64
	v_mul_f32_e32 v2, v66, v2
	v_mul_f32_e32 v66, v52, v64
	v_mul_f32_e32 v66, v66, v61
	v_mul_f32_e32 v61, v53, v64
	v_mul_f32_e32 v67, v61, v60
	v_mul_f32_e32 v60, v54, v64
	v_mul_f32_e32 v63, v60, v63
	v_mul_f32_e32 v60, v55, v64
	v_mul_f32_e32 v64, v60, v62
	v_cvt_pk_bf16_f32 v60, v1, v65
	v_cvt_pk_bf16_f32 v61, v3, v2
	v_cvt_pk_bf16_f32 v62, v66, v67
	v_and_b32_e32 v66, 0xffff0000, v48
	v_cvt_pk_bf16_f32 v63, v63, v64
	ds_write_b128 v109, v[60:63] offset:52224
	v_lshlrev_b32_e32 v1, 16, v48
	v_mul_f32_e32 v62, v66, v66
	v_and_b32_e32 v2, 0xffff0000, v49
	v_lshlrev_b32_e32 v3, 16, v49
	v_fmac_f32_e32 v62, v1, v1
	v_pk_mul_f32 v[60:61], v[2:3], v[2:3]
	s_nop 0
	v_add_f32_e32 v61, v61, v62
	v_add_f32_e32 v64, v60, v61
	v_and_b32_e32 v60, 0xffff0000, v50
	v_lshlrev_b32_e32 v61, 16, v50
	v_pk_mul_f32 v[62:63], v[60:61], v[60:61]
	s_nop 0
	v_add_f32_e32 v63, v63, v64
	v_add_f32_e32 v67, v62, v63
	v_and_b32_e32 v62, 0xffff0000, v51
	v_lshlrev_b32_e32 v63, 16, v51
	v_pk_mul_f32 v[64:65], v[62:63], v[62:63]
	s_nop 0
	v_add_f32_e32 v65, v65, v67
	v_add_f32_e32 v64, v64, v65
	s_nop 1
	v_add_f32_dpp v64, v64, v64 quad_perm:[1,0,3,2] row_mask:0xf bank_mask:0xf
	s_nop 1
	v_add_f32_dpp v64, v64, v64 quad_perm:[2,3,0,1] row_mask:0xf bank_mask:0xf
	s_nop 1
	v_add_f32_dpp v64, v64, v64 row_half_mirror row_mask:0xf bank_mask:0xf
	s_nop 1
	v_add_f32_dpp v64, v64, v64 row_mirror row_mask:0xf bank_mask:0xf
	v_fmamk_f32 v64, v64, 0x3c000000, v185
	v_cmp_gt_f32_e32 vcc, s36, v64
	v_mul_f32_e32 v65, 0x4b800000, v64
	s_nop 0
	v_cndmask_b32_e32 v64, v64, v65, vcc
	v_rsq_f32_e32 v64, v64
	s_nop 0
	v_mul_f32_e32 v65, 0x45800000, v64
	v_cndmask_b32_e32 v64, v64, v65, vcc
	v_mul_f32_e32 v56, v56, v64
	v_mul_f32_e32 v1, v56, v1
	v_mul_f32_e32 v56, v57, v64
	v_mul_f32_e32 v57, v58, v64
	v_mul_f32_e32 v3, v57, v3
	v_mul_f32_e32 v57, v59, v64
	v_mul_f32_e32 v52, v52, v64
	v_mul_f32_e32 v2, v57, v2
	v_mul_f32_e32 v57, v52, v61
	v_mul_f32_e32 v52, v53, v64
	v_mul_f32_e32 v58, v52, v60
	v_mul_f32_e32 v52, v54, v64
	v_mul_f32_e32 v59, v52, v63
	v_mul_f32_e32 v52, v55, v64
	v_mul_f32_e32 v56, v56, v66
	v_mul_f32_e32 v55, v52, v62
	v_cvt_pk_bf16_f32 v52, v1, v56
	v_add_u32_e32 v1, 0xffffff80, v130
	v_add_u32_e32 v1, s20, v1
	v_cvt_pk_bf16_f32 v53, v3, v2
	v_cvt_pk_bf16_f32 v54, v57, v58
	v_cvt_pk_bf16_f32 v55, v59, v55
	ds_write_b128 v109, v[52:55] offset:60928
	v_cmp_lt_i32_e32 vcc, -1, v1
	v_mov_b32_e32 v52, 0
	v_lshlrev_b32_e32 v2, 1, v104
	v_mov_b32_e32 v56, 0
	v_mov_b32_e32 v57, 0
	v_mov_b32_e32 v58, 0
	v_mov_b32_e32 v59, 0
	s_waitcnt lgkmcnt(0)
	s_barrier
	s_and_saveexec_b64 s[12:13], vcc
	s_cbranch_execz .LBB0_331
	v_lshlrev_b32_e32 v3, s18, v1
	v_add_u32_e32 v3, s19, v3
	v_mov_b64_e32 v[54:55], s[90:91]
	v_mad_u64_u32 v[54:55], vcc, v3, s33, v[54:55]
	v_lshl_add_u64 v[54:55], s[92:93], 1, v[54:55]
	v_mov_b32_e32 v3, v0
	v_lshl_add_u64 v[54:55], v[54:55], 0, v[2:3]
	v_add_co_u32_e32 v54, vcc, 0x1000, v54
	s_nop 1
	v_addc_co_u32_e32 v55, vcc, 0, v55, vcc
	global_load_dwordx4 v[56:59], v[54:55], off offset:2048
